# last-layer out-proj epilogue: residual loads of row groups 1-3 hoisted to the epilogue top into dead fragment regs (1 exposed round trip instead of 4)
# baseline (speedup 1.0000x reference)
.LBB0_681:
	s_ashr_i32 s59, s58, 31
	s_mul_i32 s35, s58, 0x2c0000
	s_mul_hi_i32 s12, s58, 0x2c0000
	s_add_u32 s35, s19, s35
	v_mov_b32_e32 v148, v200
	s_movk_i32 s5, 0x1600
	s_addc_u32 s12, s25, s12
	s_ashr_i32 s61, s60, 31
	s_lshl_b64 s[72:73], s[60:61], 9
	v_mul_lo_u32 v26, v148, s5
	v_or_b32_e32 v26, v26, v203
	s_add_u32 s72, s35, s72
	v_lshlrev_b32_e32 v26, 1, v26
	s_addc_u32 s73, s12, s73
	v_lshl_add_u64 v[132:133], s[72:73], 0, v[26:27]
	v_add_co_u32_e32 v134, vcc, s6, v132
	s_mov_b64 s[72:73], 0x2400
	s_nop 0
	v_addc_co_u32_e32 v135, vcc, 0, v133, vcc
	v_lshl_add_u64 v[142:143], v[132:133], 0, s[72:73]
	global_load_dwordx4 v[144:147], v[134:135], off offset:1024
	global_load_dwordx4 v[150:153], v[142:143], off offset:256
	s_mov_b32 s5, 0x2e000
	v_add_co_u32_e32 v132, vcc, s5, v132
	v_and_b32_e32 v140, 64, v224
	s_nop 0
	v_addc_co_u32_e32 v133, vcc, 0, v133, vcc
	global_load_dwordx4 v[136:139], v[132:133], off offset:1024
	s_nop 0
	global_load_dwordx4 v[132:135], v[132:133], off offset:1280
	v_add_co_u32_e32 v248, vcc, 0x58000, v142
	s_nop 1
	v_addc_co_u32_e32 v249, vcc, 0, v143, vcc
	global_load_dwordx4 v[206:209], v[248:249], off
	global_load_dwordx4 v[210:213], v[248:249], off offset:256
	v_add_co_u32_e32 v248, vcc, 0x84000, v142
	s_nop 1
	v_addc_co_u32_e32 v249, vcc, 0, v143, vcc
	global_load_dwordx4 v[214:217], v[248:249], off
	global_load_dwordx4 v[226:229], v[248:249], off offset:256
	v_add_co_u32_e32 v248, vcc, 0x160000, v142
	s_nop 1
	v_addc_co_u32_e32 v249, vcc, 0, v143, vcc
	global_load_dwordx4 v[192:195], v[248:249], off
	global_load_dwordx4 v[196:199], v[248:249], off offset:256
	v_add_co_u32_e32 v248, vcc, 0x18c000, v142
	s_nop 1
	v_addc_co_u32_e32 v249, vcc, 0, v143, vcc
	global_load_dwordx4 v[236:239], v[248:249], off
	global_load_dwordx4 v[240:243], v[248:249], off offset:256
	v_xor_b32_e32 v26, 16, v224
	v_add_u32_e32 v149, 64, v140
	v_cmp_lt_i32_e32 vcc, v26, v149
	s_lshl_b64 s[72:73], s[58:59], 14
	s_add_u32 s74, s4, s72
	v_cndmask_b32_e32 v26, v224, v26, vcc
	v_lshlrev_b32_e32 v204, 2, v26
	v_readlane_b32 s5, v251, 18
	s_addc_u32 s75, s5, s73
	s_lshl_b32 s72, s60, 2
	s_ashr_i32 s73, s72, 31
	s_lshl_b64 s[72:73], s[72:73], 2
	s_add_u32 s12, s74, s72
	s_addc_u32 s35, s75, s73
	s_add_u32 s72, s12, s68
	s_addc_u32 s73, s35, 0
	s_waitcnt vmcnt(8)
	v_lshlrev_b32_e32 v140, 16, v144
	v_and_b32_e32 v141, 0xffff0000, v144
	v_lshlrev_b32_e32 v144, 16, v145
	v_and_b32_e32 v145, 0xffff0000, v145
	v_lshlrev_b32_e32 v156, 16, v150
	v_and_b32_e32 v157, 0xffff0000, v150
	v_lshlrev_b32_e32 v150, 16, v151
	v_and_b32_e32 v151, 0xffff0000, v151
	v_lshlrev_b32_e32 v154, 16, v146
	v_and_b32_e32 v155, 0xffff0000, v146
	v_lshlrev_b32_e32 v146, 16, v147
	v_and_b32_e32 v147, 0xffff0000, v147
	v_lshlrev_b32_e32 v158, 16, v152
	v_and_b32_e32 v159, 0xffff0000, v152
	v_pk_add_f32 v[4:5], v[4:5], v[144:145]
	v_pk_add_f32 v[2:3], v[2:3], v[140:141]
	v_pk_add_f32 v[38:39], v[38:39], v[150:151]
	v_pk_add_f32 v[36:37], v[36:37], v[156:157]
	v_lshlrev_b32_e32 v152, 16, v153
	v_and_b32_e32 v153, 0xffff0000, v153
	v_pk_add_f32 v[8:9], v[8:9], v[146:147]
	v_pk_add_f32 v[6:7], v[6:7], v[154:155]
	v_pk_add_f32 v[40:41], v[40:41], v[158:159]
	v_mul_f32_e32 v26, v3, v3
	v_mul_f32_e32 v140, v5, v5
	v_mul_f32_e32 v145, v37, v37
	v_mul_f32_e32 v146, v39, v39
	v_pk_add_f32 v[42:43], v[42:43], v[152:153]
	v_mul_f32_e32 v141, v7, v7
	v_mul_f32_e32 v147, v41, v41
	v_fmac_f32_e32 v26, v2, v2
	v_fmac_f32_e32 v140, v4, v4
	v_fmac_f32_e32 v145, v36, v36
	v_fmac_f32_e32 v146, v38, v38
	v_mul_f32_e32 v144, v9, v9
	v_mul_f32_e32 v150, v43, v43
	v_fmac_f32_e32 v141, v6, v6
	v_fmac_f32_e32 v147, v40, v40
	v_add_f32_e32 v26, v26, v140
	v_add_f32_e32 v140, v145, v146
	v_fmac_f32_e32 v144, v8, v8
	v_fmac_f32_e32 v150, v42, v42
	v_add_f32_e32 v26, v141, v26
	v_add_f32_e32 v140, v147, v140
	v_add_f32_e32 v26, v144, v26
	v_add_f32_e32 v140, v150, v140
	v_add_f32_e32 v26, v26, v140
	ds_bpermute_b32 v140, v204, v26
	v_xor_b32_e32 v141, 32, v224
	v_cmp_lt_i32_e32 vcc, v141, v149
	s_waitcnt lgkmcnt(0)
	v_add_f32_e32 v144, v26, v140
	v_cndmask_b32_e32 v141, v224, v141, vcc
	v_lshlrev_b32_e32 v205, 2, v141
	ds_bpermute_b32 v145, v205, v144
	v_lshlrev_b32_e32 v26, 6, v148
	v_lshl_add_u64 v[140:141], s[72:73], 0, v[26:27]
	s_and_saveexec_b64 s[76:77], s[0:1]
	s_cbranch_execz .LBB0_683
	s_waitcnt lgkmcnt(0)
	v_add_f32_e32 v144, v144, v145
	global_store_dword v[140:141], v144, off sc1

.LBB0_685:
	s_or_b64 exec, exec, s[76:77]
	s_waitcnt lgkmcnt(0)
	s_waitcnt vmcnt(4)
	v_mov_b64_e32 v[144:145], v[206:207]
	v_mov_b64_e32 v[146:147], v[208:209]
	v_mov_b64_e32 v[150:151], v[210:211]
	v_mov_b64_e32 v[152:153], v[212:213]
	v_mov_b64_e32 v[136:137], v[214:215]
	v_mov_b64_e32 v[138:139], v[216:217]
	v_mov_b64_e32 v[132:133], v[226:227]
	v_mov_b64_e32 v[134:135], v[228:229]
	v_add_co_u32_e32 v248, vcc, 0x1b8000, v142
	s_nop 1
	v_addc_co_u32_e32 v249, vcc, 0, v143, vcc
	global_load_dwordx4 v[206:209], v[248:249], off
	global_load_dwordx4 v[210:213], v[248:249], off offset:256
	v_add_co_u32_e32 v248, vcc, 0x1e4000, v142
	s_nop 1
	v_addc_co_u32_e32 v249, vcc, 0, v143, vcc
	global_load_dwordx4 v[214:217], v[248:249], off
	global_load_dwordx4 v[226:229], v[248:249], off offset:256
	v_lshlrev_b32_e32 v154, 16, v144
	v_and_b32_e32 v155, 0xffff0000, v144
	v_lshlrev_b32_e32 v144, 16, v145
	v_and_b32_e32 v145, 0xffff0000, v145
	v_lshlrev_b32_e32 v158, 16, v150
	v_and_b32_e32 v159, 0xffff0000, v150
	v_lshlrev_b32_e32 v150, 16, v151
	v_and_b32_e32 v151, 0xffff0000, v151
	v_lshlrev_b32_e32 v156, 16, v146
	v_and_b32_e32 v157, 0xffff0000, v146
	v_lshlrev_b32_e32 v160, 16, v152
	v_and_b32_e32 v161, 0xffff0000, v152
	v_pk_add_f32 v[20:21], v[20:21], v[144:145]
	v_pk_add_f32 v[18:19], v[18:19], v[154:155]
	v_pk_add_f32 v[54:55], v[54:55], v[150:151]
	v_pk_add_f32 v[52:53], v[52:53], v[158:159]
	v_lshlrev_b32_e32 v146, 16, v147
	v_and_b32_e32 v147, 0xffff0000, v147
	v_lshlrev_b32_e32 v152, 16, v153
	v_and_b32_e32 v153, 0xffff0000, v153
	v_pk_add_f32 v[22:23], v[22:23], v[156:157]
	v_pk_add_f32 v[56:57], v[56:57], v[160:161]
	v_mul_f32_e32 v144, v19, v19
	v_mul_f32_e32 v145, v21, v21
	v_mul_f32_e32 v149, v53, v53
	v_mul_f32_e32 v150, v55, v55
	v_pk_add_f32 v[24:25], v[24:25], v[146:147]
	v_pk_add_f32 v[58:59], v[58:59], v[152:153]
	v_mul_f32_e32 v146, v23, v23
	v_mul_f32_e32 v151, v57, v57
	v_fmac_f32_e32 v144, v18, v18
	v_fmac_f32_e32 v145, v20, v20
	v_fmac_f32_e32 v149, v52, v52
	v_fmac_f32_e32 v150, v54, v54
	v_mul_f32_e32 v147, v25, v25
	v_mul_f32_e32 v152, v59, v59
	v_fmac_f32_e32 v146, v22, v22
	v_fmac_f32_e32 v151, v56, v56
	v_add_f32_e32 v144, v144, v145
	v_add_f32_e32 v145, v149, v150
	v_fmac_f32_e32 v147, v24, v24
	v_fmac_f32_e32 v152, v58, v58
	v_add_f32_e32 v144, v146, v144
	v_add_f32_e32 v145, v151, v145
	v_add_f32_e32 v144, v147, v144
	v_add_f32_e32 v145, v152, v145
	v_add_f32_e32 v144, v144, v145
	ds_bpermute_b32 v145, v204, v144
	s_waitcnt lgkmcnt(0)
	v_add_f32_e32 v144, v144, v145
	ds_bpermute_b32 v145, v205, v144
	s_and_saveexec_b64 s[76:77], s[0:1]
	s_cbranch_execz .LBB0_687
	s_waitcnt lgkmcnt(0)
	v_add_f32_e32 v144, v144, v145
	global_store_dword v[140:141], v144, off offset:2048 sc1
.LBB0_687:
	s_or_b64 exec, exec, s[76:77]
	v_lshlrev_b32_e32 v144, 16, v136
	s_waitcnt lgkmcnt(0)
	v_and_b32_e32 v145, 0xffff0000, v136
	v_lshlrev_b32_e32 v136, 16, v137
	v_and_b32_e32 v137, 0xffff0000, v137
	v_lshlrev_b32_e32 v150, 16, v132
	v_and_b32_e32 v151, 0xffff0000, v132
	v_lshlrev_b32_e32 v132, 16, v133
	v_and_b32_e32 v133, 0xffff0000, v133
	v_pk_add_f32 v[30:31], v[30:31], v[136:137]
	v_pk_add_f32 v[28:29], v[28:29], v[144:145]
	v_pk_add_f32 v[62:63], v[62:63], v[132:133]
	v_pk_add_f32 v[60:61], v[60:61], v[150:151]
	v_lshlrev_b32_e32 v146, 16, v138
	v_and_b32_e32 v147, 0xffff0000, v138
	v_lshlrev_b32_e32 v152, 16, v134
	v_and_b32_e32 v153, 0xffff0000, v134
	v_mul_f32_e32 v136, v29, v29
	v_mul_f32_e32 v137, v31, v31
	v_mul_f32_e32 v132, v61, v61
	v_mul_f32_e32 v133, v63, v63
	v_pk_add_f32 v[32:33], v[32:33], v[146:147]
	v_fmac_f32_e32 v136, v28, v28
	v_fmac_f32_e32 v137, v30, v30
	v_pk_add_f32 v[64:65], v[64:65], v[152:153]
	v_fmac_f32_e32 v132, v60, v60
	v_fmac_f32_e32 v133, v62, v62
	v_lshlrev_b32_e32 v138, 16, v139
	v_and_b32_e32 v139, 0xffff0000, v139
	v_lshlrev_b32_e32 v134, 16, v135
	v_and_b32_e32 v135, 0xffff0000, v135
	v_add_f32_e32 v136, v136, v137
	v_mul_f32_e32 v137, v33, v33
	v_add_f32_e32 v132, v132, v133
	v_mul_f32_e32 v133, v65, v65
	v_pk_add_f32 v[34:35], v[34:35], v[138:139]
	v_fmac_f32_e32 v137, v32, v32
	v_pk_add_f32 v[66:67], v[66:67], v[134:135]
	v_fmac_f32_e32 v133, v64, v64
	v_add_f32_e32 v136, v137, v136
	v_mul_f32_e32 v137, v35, v35
	v_add_f32_e32 v132, v133, v132
	v_mul_f32_e32 v133, v67, v67
	v_fmac_f32_e32 v137, v34, v34
	v_fmac_f32_e32 v133, v66, v66
	v_add_f32_e32 v136, v137, v136
	v_add_f32_e32 v132, v133, v132
	v_add_f32_e32 v132, v136, v132
	ds_bpermute_b32 v133, v204, v132
	s_waitcnt lgkmcnt(0)
	v_add_f32_e32 v132, v132, v133
	ds_bpermute_b32 v133, v205, v132
	s_and_saveexec_b64 s[76:77], s[0:1]
	s_cbranch_execz .LBB0_689
	s_waitcnt lgkmcnt(0)
	v_add_f32_e32 v132, v132, v133
	global_store_dword v[140:141], v132, off offset:3072 sc1
.LBB0_689:
	s_or_b64 exec, exec, s[76:77]
	s_waitcnt lgkmcnt(0)
	s_waitcnt vmcnt(4)
	v_mov_b64_e32 v[144:145], v[192:193]
	v_mov_b64_e32 v[146:147], v[194:195]
	v_mov_b64_e32 v[150:151], v[196:197]
	v_mov_b64_e32 v[152:153], v[198:199]
	v_mov_b64_e32 v[136:137], v[236:237]
	v_mov_b64_e32 v[138:139], v[238:239]
	v_mov_b64_e32 v[132:133], v[240:241]
	v_mov_b64_e32 v[134:135], v[242:243]
	v_lshlrev_b32_e32 v154, 16, v144
	v_and_b32_e32 v155, 0xffff0000, v144
	v_lshlrev_b32_e32 v144, 16, v145
	v_and_b32_e32 v145, 0xffff0000, v145
	v_lshlrev_b32_e32 v158, 16, v150
	v_and_b32_e32 v159, 0xffff0000, v150
	v_lshlrev_b32_e32 v150, 16, v151
	v_and_b32_e32 v151, 0xffff0000, v151
	v_lshlrev_b32_e32 v156, 16, v146
	v_and_b32_e32 v157, 0xffff0000, v146
	v_lshlrev_b32_e32 v160, 16, v152
	v_and_b32_e32 v161, 0xffff0000, v152
	v_pk_add_f32 v[70:71], v[70:71], v[144:145]
	v_pk_add_f32 v[68:69], v[68:69], v[154:155]
	v_pk_add_f32 v[102:103], v[102:103], v[150:151]
	v_pk_add_f32 v[100:101], v[100:101], v[158:159]
	v_lshlrev_b32_e32 v146, 16, v147
	v_and_b32_e32 v147, 0xffff0000, v147
	v_lshlrev_b32_e32 v152, 16, v153
	v_and_b32_e32 v153, 0xffff0000, v153
	v_pk_add_f32 v[72:73], v[72:73], v[156:157]
	v_pk_add_f32 v[104:105], v[104:105], v[160:161]
	v_mul_f32_e32 v144, v69, v69
	v_mul_f32_e32 v145, v71, v71
	v_mul_f32_e32 v149, v101, v101
	v_mul_f32_e32 v150, v103, v103
	v_pk_add_f32 v[74:75], v[74:75], v[146:147]
	v_pk_add_f32 v[106:107], v[106:107], v[152:153]
	v_mul_f32_e32 v146, v73, v73
	v_mul_f32_e32 v151, v105, v105
	v_fmac_f32_e32 v144, v68, v68
	v_fmac_f32_e32 v145, v70, v70
	v_fmac_f32_e32 v149, v100, v100
	v_fmac_f32_e32 v150, v102, v102
	v_mul_f32_e32 v147, v75, v75
	v_mul_f32_e32 v152, v107, v107
	v_fmac_f32_e32 v146, v72, v72
	v_fmac_f32_e32 v151, v104, v104
	v_add_f32_e32 v144, v144, v145
	v_add_f32_e32 v145, v149, v150
	v_fmac_f32_e32 v147, v74, v74
	v_fmac_f32_e32 v152, v106, v106
	v_add_f32_e32 v144, v146, v144
	v_add_f32_e32 v145, v151, v145
	v_add_f32_e32 v144, v147, v144
	v_add_f32_e32 v145, v152, v145
	v_add_f32_e32 v144, v144, v145
	ds_bpermute_b32 v145, v204, v144
	s_waitcnt lgkmcnt(0)
	v_add_f32_e32 v144, v144, v145
	ds_bpermute_b32 v145, v205, v144
	s_and_saveexec_b64 s[76:77], s[0:1]
	s_cbranch_execz .LBB0_691
	s_waitcnt lgkmcnt(0)
	v_add_f32_e32 v146, v144, v145
	v_add_co_u32_e32 v144, vcc, 0x2000, v140
	s_nop 1
	v_addc_co_u32_e32 v145, vcc, 0, v141, vcc
	global_store_dword v[144:145], v146, off sc1
.LBB0_691:
	s_or_b64 exec, exec, s[76:77]
	v_lshlrev_b32_e32 v144, 16, v136
	s_waitcnt lgkmcnt(0)
	v_and_b32_e32 v145, 0xffff0000, v136
	v_lshlrev_b32_e32 v136, 16, v137
	v_and_b32_e32 v137, 0xffff0000, v137
	v_lshlrev_b32_e32 v150, 16, v132
	v_and_b32_e32 v151, 0xffff0000, v132
	v_lshlrev_b32_e32 v132, 16, v133
	v_and_b32_e32 v133, 0xffff0000, v133
	v_pk_add_f32 v[78:79], v[78:79], v[136:137]
	v_pk_add_f32 v[76:77], v[76:77], v[144:145]
	v_pk_add_f32 v[110:111], v[110:111], v[132:133]
	v_pk_add_f32 v[108:109], v[108:109], v[150:151]
	v_lshlrev_b32_e32 v146, 16, v138
	v_and_b32_e32 v147, 0xffff0000, v138
	v_lshlrev_b32_e32 v152, 16, v134
	v_and_b32_e32 v153, 0xffff0000, v134
	v_mul_f32_e32 v136, v77, v77
	v_mul_f32_e32 v137, v79, v79
	v_mul_f32_e32 v132, v109, v109
	v_mul_f32_e32 v133, v111, v111
	v_pk_add_f32 v[80:81], v[80:81], v[146:147]
	v_fmac_f32_e32 v136, v76, v76
	v_fmac_f32_e32 v137, v78, v78
	v_pk_add_f32 v[112:113], v[112:113], v[152:153]
	v_fmac_f32_e32 v132, v108, v108
	v_fmac_f32_e32 v133, v110, v110
	v_lshlrev_b32_e32 v138, 16, v139
	v_and_b32_e32 v139, 0xffff0000, v139
	v_lshlrev_b32_e32 v134, 16, v135
	v_and_b32_e32 v135, 0xffff0000, v135
	v_add_f32_e32 v136, v136, v137
	v_mul_f32_e32 v137, v81, v81
	v_add_f32_e32 v132, v132, v133
	v_mul_f32_e32 v133, v113, v113
	v_pk_add_f32 v[82:83], v[82:83], v[138:139]
	v_fmac_f32_e32 v137, v80, v80
	v_pk_add_f32 v[114:115], v[114:115], v[134:135]
	v_fmac_f32_e32 v133, v112, v112
	v_add_f32_e32 v136, v137, v136
	v_mul_f32_e32 v137, v83, v83
	v_add_f32_e32 v132, v133, v132
	v_mul_f32_e32 v133, v115, v115
	v_fmac_f32_e32 v137, v82, v82
	v_fmac_f32_e32 v133, v114, v114
	v_add_f32_e32 v136, v137, v136
	v_add_f32_e32 v132, v133, v132
	v_add_f32_e32 v132, v136, v132
	ds_bpermute_b32 v133, v204, v132
	s_waitcnt lgkmcnt(0)
	v_add_f32_e32 v132, v132, v133
	ds_bpermute_b32 v133, v205, v132
	s_and_saveexec_b64 s[76:77], s[0:1]
	s_cbranch_execz .LBB0_693
	s_waitcnt lgkmcnt(0)
	v_add_f32_e32 v134, v132, v133
	v_add_co_u32_e32 v132, vcc, 0x2000, v140
	s_nop 1
	v_addc_co_u32_e32 v133, vcc, 0, v141, vcc
	global_store_dword v[132:133], v134, off offset:1024 sc1
.LBB0_693:
	s_or_b64 exec, exec, s[76:77]
	s_waitcnt lgkmcnt(0)
	s_waitcnt vmcnt(0)
	v_mov_b64_e32 v[144:145], v[206:207]
	v_mov_b64_e32 v[146:147], v[208:209]
	v_mov_b64_e32 v[150:151], v[210:211]
	v_mov_b64_e32 v[152:153], v[212:213]
	v_mov_b64_e32 v[136:137], v[214:215]
	v_mov_b64_e32 v[138:139], v[216:217]
	v_mov_b64_e32 v[132:133], v[226:227]
	v_mov_b64_e32 v[134:135], v[228:229]
	v_lshlrev_b32_e32 v142, 16, v144
	v_and_b32_e32 v143, 0xffff0000, v144
	v_lshlrev_b32_e32 v144, 16, v145
	v_and_b32_e32 v145, 0xffff0000, v145
	v_lshlrev_b32_e32 v156, 16, v150
	v_and_b32_e32 v157, 0xffff0000, v150
	v_lshlrev_b32_e32 v150, 16, v151
	v_and_b32_e32 v151, 0xffff0000, v151
	v_lshlrev_b32_e32 v154, 16, v146
	v_and_b32_e32 v155, 0xffff0000, v146
	v_lshlrev_b32_e32 v146, 16, v147
	v_and_b32_e32 v147, 0xffff0000, v147
	v_lshlrev_b32_e32 v158, 16, v152
	v_and_b32_e32 v159, 0xffff0000, v152
	v_pk_add_f32 v[86:87], v[86:87], v[144:145]
	v_pk_add_f32 v[84:85], v[84:85], v[142:143]
	v_pk_add_f32 v[118:119], v[118:119], v[150:151]
	v_pk_add_f32 v[116:117], v[116:117], v[156:157]
	v_lshlrev_b32_e32 v152, 16, v153
	v_and_b32_e32 v153, 0xffff0000, v153
	v_pk_add_f32 v[90:91], v[90:91], v[146:147]
	v_pk_add_f32 v[88:89], v[88:89], v[154:155]
	v_pk_add_f32 v[120:121], v[120:121], v[158:159]
	v_mul_f32_e32 v142, v85, v85
	v_mul_f32_e32 v143, v87, v87
	v_mul_f32_e32 v146, v117, v117
	v_mul_f32_e32 v147, v119, v119
	v_pk_add_f32 v[122:123], v[122:123], v[152:153]
	v_mul_f32_e32 v144, v89, v89
	v_mul_f32_e32 v149, v121, v121
	v_fmac_f32_e32 v142, v84, v84
	v_fmac_f32_e32 v143, v86, v86
	v_fmac_f32_e32 v146, v116, v116
	v_fmac_f32_e32 v147, v118, v118
	v_mul_f32_e32 v145, v91, v91
	v_mul_f32_e32 v150, v123, v123
	v_fmac_f32_e32 v144, v88, v88
	v_fmac_f32_e32 v149, v120, v120
	v_add_f32_e32 v142, v142, v143
	v_add_f32_e32 v143, v146, v147
	v_fmac_f32_e32 v145, v90, v90
	v_fmac_f32_e32 v150, v122, v122
	v_add_f32_e32 v142, v144, v142
	v_add_f32_e32 v143, v149, v143
	v_add_f32_e32 v142, v145, v142
	v_add_f32_e32 v143, v150, v143
	v_add_f32_e32 v142, v142, v143
	ds_bpermute_b32 v143, v204, v142
	s_waitcnt lgkmcnt(0)
	v_add_f32_e32 v142, v142, v143
	ds_bpermute_b32 v143, v205, v142
	s_and_saveexec_b64 s[76:77], s[0:1]
	s_cbranch_execz .LBB0_695
	s_waitcnt lgkmcnt(0)
	v_add_f32_e32 v144, v142, v143
	v_add_co_u32_e32 v142, vcc, 0x2000, v140
	s_nop 1
	v_addc_co_u32_e32 v143, vcc, 0, v141, vcc
	global_store_dword v[142:143], v144, off offset:2048 sc1
.LBB0_695:
	s_or_b64 exec, exec, s[76:77]
	v_lshlrev_b32_e32 v142, 16, v136
	s_waitcnt lgkmcnt(0)
	v_and_b32_e32 v143, 0xffff0000, v136
	v_lshlrev_b32_e32 v136, 16, v137
	v_and_b32_e32 v137, 0xffff0000, v137
	v_lshlrev_b32_e32 v146, 16, v132
	v_and_b32_e32 v147, 0xffff0000, v132
	v_lshlrev_b32_e32 v132, 16, v133
	v_and_b32_e32 v133, 0xffff0000, v133
	v_pk_add_f32 v[94:95], v[94:95], v[136:137]
	v_pk_add_f32 v[92:93], v[92:93], v[142:143]
	v_pk_add_f32 v[126:127], v[126:127], v[132:133]
	v_pk_add_f32 v[124:125], v[124:125], v[146:147]
	v_lshlrev_b32_e32 v144, 16, v138
	v_and_b32_e32 v145, 0xffff0000, v138
	v_lshlrev_b32_e32 v150, 16, v134
	v_and_b32_e32 v151, 0xffff0000, v134
	v_mul_f32_e32 v136, v93, v93
	v_mul_f32_e32 v137, v95, v95
	v_mul_f32_e32 v132, v125, v125
	v_mul_f32_e32 v133, v127, v127
	v_pk_add_f32 v[96:97], v[96:97], v[144:145]
	v_fmac_f32_e32 v136, v92, v92
	v_fmac_f32_e32 v137, v94, v94
	v_pk_add_f32 v[128:129], v[128:129], v[150:151]
	v_fmac_f32_e32 v132, v124, v124
	v_fmac_f32_e32 v133, v126, v126
	v_lshlrev_b32_e32 v138, 16, v139
	v_and_b32_e32 v139, 0xffff0000, v139
	v_lshlrev_b32_e32 v134, 16, v135
	v_and_b32_e32 v135, 0xffff0000, v135
	v_add_f32_e32 v136, v136, v137
	v_mul_f32_e32 v137, v97, v97
	v_add_f32_e32 v132, v132, v133
	v_mul_f32_e32 v133, v129, v129
	v_pk_add_f32 v[98:99], v[98:99], v[138:139]
	v_fmac_f32_e32 v137, v96, v96
	v_pk_add_f32 v[130:131], v[130:131], v[134:135]
	v_fmac_f32_e32 v133, v128, v128
	v_add_f32_e32 v136, v137, v136
	v_mul_f32_e32 v137, v99, v99
	v_add_f32_e32 v132, v133, v132
	v_mul_f32_e32 v133, v131, v131
	v_fmac_f32_e32 v137, v98, v98
	v_fmac_f32_e32 v133, v130, v130
	v_add_f32_e32 v136, v137, v136
	v_add_f32_e32 v132, v133, v132
	v_add_f32_e32 v132, v136, v132
	ds_bpermute_b32 v133, v204, v132
	s_waitcnt lgkmcnt(0)
	v_add_f32_e32 v132, v132, v133
	ds_bpermute_b32 v133, v205, v132
	s_and_saveexec_b64 s[76:77], s[0:1]
	s_cbranch_execz .LBB0_697
	s_waitcnt lgkmcnt(0)
	v_add_f32_e32 v134, v132, v133
	v_add_co_u32_e32 v132, vcc, 0x2000, v140
	s_nop 1
	v_addc_co_u32_e32 v133, vcc, 0, v141, vcc
	global_store_dword v[132:133], v134, off offset:3072 sc1
